# v91 + GDN scan: one static priority raise for the younger wave half (waves 4-7), first half without store waits, alternating MFMA pairs in the second half
# speedup vs baseline: 1.0023x; 1.0023x over previous
; #define LAS __attribute__((address_space(3)))
; __device__ __forceinline__ void lds_barrier() { asm volatile("s_waitcnt lgkmcnt(0)" ::: "memory"); __builtin_amdgcn_s_barrier(); asm volatile("" ::: "memory"); }
; __device__ __forceinline__ void gdn_chain(LAS unsigned char* lds, const GdnP& P, const float* out_norm, int bh, const int tid) {
;     const int w = __builtin_amdgcn_readfirstlane(tid >> 6), lane = tid & 63, l15 = lane & 15, quad = lane >> 4;
;     const int b = bh >> 3, h = bh & 7, mt = w & 3, nh = w >> 2;
;     f32x4 sacc[8];
; #pragma unroll
;     for (int n = 0; n < 8; ++n) sacc[n] = (f32x4){0.f, 0.f, 0.f, 0.f};
;     lds_barrier();
;     for (int i = tid; i < 34816 / 16; i += 512) *(LAS u32x4*)(lds + GC_ST + i * 16) = (u32x4){0u, 0u, 0u, 0u};
;     ChainOps cur, nxt;
;     chain_load(cur, P, b, h, 0, w, mt, nh, lane, tid);
;     lds_barrier();
;     for (int n = 0; n < 64; ++n) {
.LBB0_1121:
	v_readfirstlane_b32 s32, v205
	s_cmpk_lt_u32 s32, 0x100
	s_cbranch_scc1 .Lcprio_skip
	s_setprio 1

; __device__ __forceinline__ void chain_load(ChainOps& o, const GdnP& P, int b, int h, int n, int w, int mt, int nh, int lane, int tid) {
;     const int l15 = lane & 15, quad = lane >> 4;
;     const int cn = b * 64 + n, unit = cn * 8 + h, row0 = cn * 64;
;     const bf16_t* wrow = P.wbuf + (size_t)unit * 8192 + (mt * 16 + l15) * 128 + quad * 8;
;     const bf16_t* qrow = P.proj + (size_t)(row0 + mt * 16 + l15) * NIN + C_GDN + h * 128 + quad * 8;
; #pragma unroll
;     for (int s = 0; s < 4; ++s) { o.wf[s] = *(const bf16x8*)(wrow + 32 * s); o.qf[s] = *(const bf16x8*)(qrow + 32 * s); }
;     const bf16_t* arow = P.attnb + (size_t)unit * 4096 + (mt * 16 + l15) * 64 + quad * 8;
;     const int kidx = w * 16 + l15;
;     const bf16_t* krow = P.proj + (size_t)(row0 + (kidx >> 1)) * NIN + C_GDN + 1024 + h * 128 + (kidx & 1) * 64 + quad * 8;
; #pragma unroll
;     for (int s = 0; s < 2; ++s) { o.af[s] = *(const bf16x8*)(arow + 32 * s); o.kf[s] = *(const bf16x8*)(krow + 32 * s); }
;     o.cd = P.cdb[unit];
;     const int cb = ((mt * 2 + nh) * 64 + lane) * 2;
;     const bf16_t* up = P.proj + (size_t)(row0 + (cb >> 4)) * NIN + C_GDN + 2048 + h * 128 + (cb & 15) * 8;
;     o.uf[0] = *(const u32x4*)up; o.uf[1] = *(const u32x4*)(up + 8);
; __device__ __forceinline__ void gdn_chain(LAS unsigned char* lds, const GdnP& P, const float* out_norm, int bh, const int tid) {
;     ...
;     for (int n = 0; n < 64; ++n) {
;         const int row0 = (b * 64 + n) * 64;
;         chain_load(nxt, P, b, h, n < 63 ? n + 1 : n, w, mt, nh, lane, tid);
;         f32x4 oacc[4];
; #pragma unroll
;         for (int q = 0; q < 4; ++q) { const int nt = 4 * nh + q; f32x4 a1 = (f32x4){0.f, 0.f, 0.f, 0.f}; oacc[q] = (f32x4){0.f, 0.f, 0.f, 0.f};
; #pragma unroll
;             for (int s = 0; s < 4; ++s) { const bf16x8 sf = *(const LAS bf16x8*)(lds + GC_ST + (nt * 16 + l15) * 272 + (quad * 8 + 32 * s) * 2);
;                 a1 = __builtin_amdgcn_mfma_f32_16x16x32_bf16(cur.wf[s], sf, a1, 0, 0, 0); oacc[q] = __builtin_amdgcn_mfma_f32_16x16x32_bf16(cur.qf[s], sf, oacc[q], 0, 0, 0); }
;             const unsigned u01 = cur.uf[q >> 1][(q & 1) * 2], u23 = cur.uf[q >> 1][(q & 1) * 2 + 1];
;             u32x2 pv; pv.x = pk2(bflo(u01) - a1[0], bfhi(u01) - a1[1]); pv.y = pk2(bflo(u23) - a1[2], bfhi(u23) - a1[3]);
;             *(LAS u32x2*)(lds + GC_VT + (nt * 16 + l15) * 144 + (mt * 16 + quad * 4) * 2) = pv; }
.LBB0_1126:
	s_waitcnt vmcnt(4)
	v_mov_b64_e32 v[90:91], v[74:75]
	v_mov_b64_e32 v[88:89], v[72:73]
	ds_read_b128 v[72:75], v161
	ds_read_b128 v[92:95], v161 offset:64
	s_waitcnt vmcnt(4)
	v_mov_b64_e32 v[106:107], v[14:15]
	v_mov_b64_e32 v[104:105], v[12:13]
	s_waitcnt vmcnt(4)
	v_mov_b64_e32 v[110:111], v[22:23]
	s_waitcnt lgkmcnt(1)
	v_mfma_f32_16x16x32_bf16 v[96:99], v[88:91], v[72:75], 0
	s_waitcnt vmcnt(4)
	v_mov_b64_e32 v[102:103], v[30:31]
	v_mov_b64_e32 v[108:109], v[20:21]
	ds_read_b128 v[20:23], v161 offset:128
	v_mov_b64_e32 v[100:101], v[28:29]
	s_waitcnt lgkmcnt(1)
	v_mfma_f32_16x16x32_bf16 v[28:31], v[104:107], v[92:95], v[96:99]
	v_mov_b64_e32 v[180:181], v[18:19]
	v_mov_b64_e32 v[184:185], v[6:7]
	v_mov_b64_e32 v[178:179], v[16:17]
	v_mov_b64_e32 v[182:183], v[4:5]
	ds_read_b128 v[4:7], v161 offset:192
	s_waitcnt lgkmcnt(1)
	v_mfma_f32_16x16x32_bf16 v[16:19], v[108:111], v[20:23], v[28:31]
	v_mov_b64_e32 v[188:189], v[2:3]
	v_mov_b64_e32 v[186:187], v[0:1]
	s_waitcnt vmcnt(4)
	v_mov_b64_e32 v[192:193], v[10:11]
	v_mfma_f32_16x16x32_bf16 v[12:15], v[100:103], v[72:75], 0
	v_mov_b64_e32 v[190:191], v[8:9]
	s_waitcnt vmcnt(4)
	v_lshlrev_b32_e32 v8, 16, v80
	v_and_b32_e32 v9, 0xffff0000, v80
	s_waitcnt lgkmcnt(0)
	v_mfma_f32_16x16x32_bf16 v[0:3], v[178:181], v[4:7], v[16:19]
	s_add_i32 s0, s47, 0x41
	s_cmp_lg_u32 s47, -1
	s_cselect_b32 s0, s0, 63
	s_add_i32 s0, s0, s44
	s_lshl_b32 s30, s0, 3
	s_nop 2
	v_pk_add_f32 v[0:1], v[8:9], v[0:1] neg_lo:[0,1] neg_hi:[0,1]
	v_mfma_f32_16x16x32_bf16 v[8:11], v[182:185], v[92:95], v[12:15]
	v_cvt_pk_bf16_f32 v0, v0, v1
	s_or_b32 s30, s30, s43
	s_lshl_b32 s50, s0, 6
	v_lshlrev_b32_e32 v12, 16, v81
	v_and_b32_e32 v13, 0xffff0000, v81
	v_pk_add_f32 v[2:3], v[12:13], v[2:3] neg_lo:[0,1] neg_hi:[0,1]
	v_mfma_f32_16x16x32_bf16 v[8:11], v[186:189], v[20:23], v[8:11]
	v_cvt_pk_bf16_f32 v1, v2, v3
	v_add_u32_e32 v2, v155, v156
	ds_write_b64 v2, v[0:1] offset:34816
	ds_read_b128 v[0:3], v162
	v_mfma_f32_16x16x32_bf16 v[198:201], v[190:193], v[4:7], v[8:11]
	ds_read_b128 v[4:7], v162 offset:64
	ds_read_b128 v[12:15], v162 offset:128
	s_ashr_i32 s31, s30, 31
	s_waitcnt lgkmcnt(2)
	v_mfma_f32_16x16x32_bf16 v[8:11], v[88:91], v[0:3], 0
	v_mov_b64_e32 v[94:95], v[38:39]
	s_lshl_b64 s[48:49], s[30:31], 14
	v_or_b32_e32 v18, s50, v152
	v_mfma_f32_16x16x32_bf16 v[0:3], v[100:103], v[0:3], 0
	v_mov_b64_e32 v[202:203], s[16:17]
	v_mov_b64_e32 v[92:93], v[36:37]
	v_lshl_add_u64 v[16:17], v[132:133], 0, s[48:49]
	s_waitcnt lgkmcnt(1)
	v_mfma_f32_16x16x32_bf16 v[8:11], v[104:107], v[4:7], v[8:11]
	s_lshl_b32 s0, s45, 1
	v_mov_b64_e32 v[196:197], v[70:71]
	v_mov_b64_e32 v[194:195], v[68:69]
	v_mfma_f32_16x16x32_bf16 v[0:3], v[182:185], v[4:7], v[0:3]
	ds_read_b128 v[4:7], v162 offset:192
	v_mov_b64_e32 v[208:209], v[46:47]
	v_mov_b64_e32 v[98:99], v[50:51]
	s_waitcnt lgkmcnt(1)
	v_mfma_f32_16x16x32_bf16 v[8:11], v[108:111], v[12:15], v[8:11]
	v_mov_b64_e32 v[206:207], v[44:45]
	v_mov_b64_e32 v[96:97], v[48:49]
	v_add_u32_e32 v80, s50, v153
	s_waitcnt lgkmcnt(0)
	v_mfma_f32_16x16x32_bf16 v[8:11], v[178:181], v[4:7], v[8:11]
	v_mov_b32_e32 v138, v123
	v_mov_b32_e32 v123, v115
	v_mov_b32_e32 v127, v115
	v_mfma_f32_16x16x32_bf16 v[0:3], v[186:189], v[12:15], v[0:3]
	v_lshlrev_b32_e32 v14, 16, v82
	v_and_b32_e32 v15, 0xffff0000, v82
	s_nop 1
	v_pk_add_f32 v[8:9], v[14:15], v[8:9] neg_lo:[0,1] neg_hi:[0,1]
	v_lshlrev_b32_e32 v14, 16, v83
	v_and_b32_e32 v15, 0xffff0000, v83
	v_pk_add_f32 v[10:11], v[14:15], v[10:11] neg_lo:[0,1] neg_hi:[0,1]
	v_cvt_pk_bf16_f32 v8, v8, v9
	v_cvt_pk_bf16_f32 v9, v10, v11
	v_add_u32_e32 v10, v155, v157
	ds_write_b64 v10, v[8:9] offset:34816
	ds_read_b128 v[8:11], v163
	ds_read_b128 v[36:39], v163 offset:64
	v_mad_i64_i32 v[12:13], s[48:49], v18, s40, v[202:203]
	v_lshl_add_u64 v[12:13], v[12:13], 0, s[0:1]
	s_waitcnt lgkmcnt(1)
	v_mfma_f32_16x16x32_bf16 v[28:31], v[88:91], v[8:11], 0
	s_lshl_b64 s[48:49], s[30:31], 13
	v_lshl_add_u64 v[218:219], v[134:135], 0, s[48:49]
	v_mad_i64_i32 v[80:81], s[48:49], v80, s40, v[202:203]
	v_mfma_f32_16x16x32_bf16 v[210:213], v[190:193], v[4:7], v[0:3]
	s_lshl_b64 s[30:31], s[30:31], 2
	s_add_u32 s30, s2, s30
	s_addc_u32 s31, s3, s31
	v_lshl_add_u64 v[0:1], v[12:13], 0, v[114:115]
	v_add_co_u32_e32 v70, vcc, s41, v0
	v_lshl_add_u64 v[68:69], v[0:1], 0, s[22:23]
	s_nop 0
	v_addc_co_u32_e32 v71, vcc, 0, v1, vcc
	global_load_dwordx4 v[72:75], v[16:17], off
	global_load_dwordx4 v[12:15], v[16:17], off offset:64
	v_mfma_f32_16x16x32_bf16 v[44:47], v[100:103], v[8:11], 0
	global_load_dwordx4 v[4:7], v[68:69], off offset:64
	global_load_dwordx4 v[0:3], v[68:69], off offset:128
	global_load_dwordx4 v[20:23], v[16:17], off offset:128
	s_nop 0
	global_load_dwordx4 v[16:19], v[16:17], off offset:192
	v_pk_mul_f32 v[66:67], v[66:67], v[138:139] op_sel_hi:[1,0]
	v_pk_mul_f32 v[64:65], v[64:65], v[138:139] op_sel_hi:[1,0]
	s_waitcnt lgkmcnt(0)
; __device__ __forceinline__ void chain_load(ChainOps& o, const GdnP& P, int b, int h, int n, int w, int mt, int nh, int lane, int tid) {
;     ...
;     for (int s = 0; s < 4; ++s) { o.wf[s] = *(const bf16x8*)(wrow + 32 * s); o.qf[s] = *(const bf16x8*)(qrow + 32 * s); }
; __device__ __forceinline__ void gdn_chain(LAS unsigned char* lds, const GdnP& P, const float* out_norm, int bh, const int tid) {
;     ...
;         for (int q = 0; q < 4; ++q) { const int nt = 4 * nh + q; f32x4 a1 = (f32x4){0.f, 0.f, 0.f, 0.f}; oacc[q] = (f32x4){0.f, 0.f, 0.f, 0.f};
; #pragma unroll
;             for (int s = 0; s < 4; ++s) { const bf16x8 sf = *(const LAS bf16x8*)(lds + GC_ST + (nt * 16 + l15) * 272 + (quad * 8 + 32 * s) * 2);
;                 a1 = __builtin_amdgcn_mfma_f32_16x16x32_bf16(cur.wf[s], sf, a1, 0, 0, 0); oacc[q] = __builtin_amdgcn_mfma_f32_16x16x32_bf16(cur.qf[s], sf, oacc[q], 0, 0, 0); }
;             const unsigned u01 = cur.uf[q >> 1][(q & 1) * 2], u23 = cur.uf[q >> 1][(q & 1) * 2 + 1];
;             u32x2 pv; pv.x = pk2(bflo(u01) - a1[0], bfhi(u01) - a1[1]); pv.y = pk2(bflo(u23) - a1[2], bfhi(u23) - a1[3]);
;             *(LAS u32x2*)(lds + GC_VT + (nt * 16 + l15) * 144 + (mt * 16 + quad * 4) * 2) = pv; }
;         lds_barrier();
;         float ss[4] = {0.f, 0.f, 0.f, 0.f};
; #pragma unroll
;         for (int q = 0; q < 4; ++q) { const int nt = 4 * nh + q;
; #pragma unroll
;             for (int s = 0; s < 2; ++s) { const bf16x8 vf = *(const LAS bf16x8*)(lds + GC_VT + (nt * 16 + l15) * 144 + (quad * 8 + 32 * s) * 2); oacc[q] = __builtin_amdgcn_mfma_f32_16x16x32_bf16(cur.af[s], vf, oacc[q], 0, 0, 0); }
; #pragma unroll
;             for (int i = 0; i < 4; ++i) { ss[i] += oacc[q][i] * oacc[q][i]; *(LAS bf16_t*)(lds + GC_OB + (mt * 16 + quad * 4 + i) * 272 + (nt * 16 + l15) * 2) = (bf16_t)f2bf(oacc[q][i]); } }
; #pragma unroll
;         for (int nt = 0; nt < 8; ++nt) { sacc[nt] = sacc[nt] * cur.cd;
; #pragma unroll
;             for (int s = 0; s < 2; ++s) { const bf16x8 vf = *(const LAS bf16x8*)(lds + GC_VT + (nt * 16 + l15) * 144 + (quad * 8 + 32 * s) * 2); sacc[nt] = __builtin_amdgcn_mfma_f32_16x16x32_bf16(cur.kf[s], vf, sacc[nt], 0, 0, 0); }
;             u32x2 pv; pv.x = pk2(sacc[nt][0], sacc[nt][1]); pv.y = pk2(sacc[nt][2], sacc[nt][3]);
;             *(LAS u32x2*)(lds + GC_ST + (nt * 16 + l15) * 272 + (w * 16 + quad * 4) * 2) = pv; }
	v_mfma_f32_16x16x32_bf16 v[48:51], v[104:107], v[36:39], v[28:31]
	s_nop 2
	global_load_dwordx4 v[28:31], v[70:71], off offset:2048
	global_load_dwordx4 v[8:11], v[68:69], off offset:192
	ds_read_b128 v[68:71], v163 offset:128
	v_pk_mul_f32 v[62:63], v[62:63], v[138:139] op_sel_hi:[1,0]
	v_mfma_f32_16x16x32_bf16 v[36:39], v[182:185], v[36:39], v[44:47]
	v_mul_f32_e64 v60, v60, v138
	v_mul_f32_e64 v61, v61, v138
	v_pk_mul_f32 v[58:59], v[58:59], v[138:139] op_sel_hi:[1,0]
	v_pk_mul_f32 v[56:57], v[56:57], v[138:139] op_sel_hi:[1,0]
	ds_read_b128 v[44:47], v163 offset:192
	s_waitcnt lgkmcnt(1)
	v_mfma_f32_16x16x32_bf16 v[48:51], v[108:111], v[68:71], v[48:51]
	v_mul_f32_e64 v54, v54, v138
	v_mul_f32_e64 v55, v55, v138
	v_pk_mul_f32 v[52:53], v[52:53], v[138:139] op_sel_hi:[1,0]
	v_pk_mul_f32 v[42:43], v[42:43], v[138:139] op_sel_hi:[1,0]
	s_waitcnt lgkmcnt(0)
	v_mfma_f32_16x16x32_bf16 v[48:51], v[178:181], v[44:47], v[48:51]
	v_mul_f32_e64 v40, v40, v138
	v_mul_f32_e64 v41, v41, v138
	v_pk_mul_f32 v[34:35], v[34:35], v[138:139] op_sel_hi:[1,0]
	v_pk_mul_f32 v[32:33], v[32:33], v[138:139] op_sel_hi:[1,0]
	v_mfma_f32_16x16x32_bf16 v[36:39], v[186:189], v[68:71], v[36:39]
	s_waitcnt vmcnt(12)
	v_lshlrev_b32_e32 v70, 16, v84
	v_and_b32_e32 v71, 0xffff0000, v84
	v_pk_add_f32 v[48:49], v[70:71], v[48:49] neg_lo:[0,1] neg_hi:[0,1]
	v_lshlrev_b32_e32 v70, 16, v85
	v_and_b32_e32 v71, 0xffff0000, v85
	v_pk_add_f32 v[50:51], v[70:71], v[50:51] neg_lo:[0,1] neg_hi:[0,1]
	v_cvt_pk_bf16_f32 v48, v48, v49
	v_cvt_pk_bf16_f32 v49, v50, v51
	v_add_u32_e32 v50, v155, v158
	ds_write_b64 v50, v[48:49] offset:34816
	ds_read_b128 v[48:51], v164
	v_lshl_add_u64 v[68:69], v[80:81], 0, s[0:1]
	ds_read_b128 v[80:83], v164 offset:64
	v_lshl_add_u64 v[68:69], v[68:69], 0, v[122:123]
	s_waitcnt lgkmcnt(1)
	v_mfma_f32_16x16x32_bf16 v[88:91], v[88:91], v[48:51], 0
	v_add_u32_e32 v84, s50, v154
	v_pk_mul_f32 v[26:27], v[26:27], v[138:139] op_sel_hi:[1,0]
	v_pk_mul_f32 v[24:25], v[24:25], v[138:139] op_sel_hi:[1,0]
	v_mfma_f32_16x16x32_bf16 v[214:217], v[190:193], v[44:47], v[36:39]
	v_mul_f32_e64 v78, v78, v138
	v_mul_f32_e64 v79, v79, v138
	v_pk_mul_f32 v[76:77], v[76:77], v[138:139] op_sel_hi:[1,0]
	v_lshl_add_u64 v[36:37], v[68:69], 0, v[114:115]
	v_lshl_add_u64 v[38:39], v[36:37], 0, s[24:25]
	v_add_co_u32_e32 v36, vcc, s38, v36
	global_load_dwordx4 v[68:71], v[218:219], off
	global_load_dwordx4 v[44:47], v[218:219], off offset:64
	v_addc_co_u32_e32 v37, vcc, 0, v37, vcc
	v_mfma_f32_16x16x32_bf16 v[100:103], v[100:103], v[48:51], 0
	global_load_dwordx4 v[48:51], v[36:37], off
	s_nop 0
	global_load_dwordx4 v[36:39], v[38:39], off offset:64
	s_nop 0
	global_load_dword v123, v115, s[30:31]
	s_waitcnt lgkmcnt(0)
	v_mfma_f32_16x16x32_bf16 v[88:91], v[104:107], v[80:83], v[88:91]
	ds_read_b128 v[104:107], v164 offset:128
	v_mad_i64_i32 v[84:85], s[30:31], v84, s40, v[202:203]
	v_mfma_f32_16x16x32_bf16 v[80:83], v[182:185], v[80:83], v[100:103]
	v_lshl_add_u64 v[84:85], v[84:85], 0, s[0:1]
	s_nop 1
	ds_read_b128 v[100:103], v164 offset:192
	s_waitcnt lgkmcnt(1)
	v_mfma_f32_16x16x32_bf16 v[88:91], v[108:111], v[104:107], v[88:91]
	v_mfma_f32_16x16x32_bf16 v[104:107], v[186:189], v[104:107], v[80:83]
	s_nop 2
	v_lshl_add_u64 v[80:81], v[84:85], 0, v[126:127]
	s_waitcnt lgkmcnt(0)
	v_mfma_f32_16x16x32_bf16 v[108:111], v[178:181], v[100:103], v[88:91]
	v_lshl_add_u64 v[84:85], v[80:81], 0, s[26:27]
	v_add_co_u32_e32 v80, vcc, s38, v80
	v_mfma_f32_16x16x32_bf16 v[178:181], v[190:193], v[100:103], v[104:107]
	s_nop 0
	v_addc_co_u32_e32 v81, vcc, 0, v81, vcc
	global_load_dwordx4 v[80:83], v[80:81], off offset:2048
	s_nop 0
	global_load_dwordx4 v[88:91], v[84:85], off offset:16
	v_lshlrev_b32_e32 v84, 16, v86
	v_and_b32_e32 v85, 0xffff0000, v86
	v_lshlrev_b32_e32 v86, 16, v87
	v_and_b32_e32 v87, 0xffff0000, v87
	v_pk_add_f32 v[84:85], v[84:85], v[108:109] neg_lo:[0,1] neg_hi:[0,1]
	v_pk_add_f32 v[86:87], v[86:87], v[110:111] neg_lo:[0,1] neg_hi:[0,1]
	v_cvt_pk_bf16_f32 v84, v84, v85
	v_cvt_pk_bf16_f32 v85, v86, v87
	v_add_u32_e32 v86, v155, v159
	ds_write_b64 v86, v[84:85] offset:34816
	s_waitcnt lgkmcnt(0)
	s_barrier
	ds_read_b128 v[182:185], v148 offset:34816
	ds_read_b128 v[186:189], v148 offset:34880
	ds_read_b128 v[190:193], v148 offset:37120
	ds_read_b128 v[232:235], v148 offset:37184
	s_waitcnt lgkmcnt(2)
	s_cmp_lg_u32 s59, 0
	s_cbranch_scc1 .Lcb_no0
	v_mfma_f32_16x16x32_bf16 v[64:67], v[96:99], v[182:185], v[64:67]
	v_mfma_f32_16x16x32_bf16 v[84:87], v[194:197], v[182:185], v[198:201]
	v_mfma_f32_16x16x32_bf16 v[64:67], v[92:95], v[186:189], v[64:67]
	v_mfma_f32_16x16x32_bf16 v[84:87], v[206:209], v[186:189], v[84:87]
	s_branch .Lcb_skip0
